# adaLN GEMV double-buffered 16-row sets; resid epilogue loads software-pipelined with counted vmcnt; final norm rewrite
# baseline (speedup 1.0000x reference)
; __device__ __forceinline__ float bf_lo(unsigned u) { return __uint_as_float(u << 16); }
; __device__ __forceinline__ float bf_hi(unsigned u) { return __uint_as_float(u & 0xffff0000u); }
; __device__ __forceinline__ u32x4 pack8(const f32x4 a, const f32x4 b) { u32x4 w; w.x = cvt_pk_bf16(a[0], a[1]); w.y = cvt_pk_bf16(a[2], a[3]); w.z = cvt_pk_bf16(b[0], b[1]); w.w = cvt_pk_bf16(b[2], b[3]); return w; }
;     __device__ __forceinline__ bool operator()(f32x4 (&acc)[2][2][4][2], const Unit& u, int wr, int wc, int fr, int fq) const {
;     ...
;         const int vec = u.pm >> 5;
;         const int row0 = u.pm * 256 + wr * 64 + fr, c0 = u.pn * 256 + wc * 32 + fq * 8;
;         const float* gp = gate + vec * 12288 + c0;
;         f32x4 gv[2][2];
; #pragma unroll
;         for (int bj = 0; bj < 2; ++bj) { gv[bj][0] = *(const f32x4*)(gp + bj * 128); gv[bj][1] = *(const f32x4*)(gp + bj * 128 + 4); }
; #pragma unroll
;         for (int b4 = 0; b4 < 4; ++b4) {
;             const int ai = b4 >> 1, mh = (b4 & 1) * 2;
;             u32x4 xq[2][2];
; #pragma unroll
;             for (int mm = 0; mm < 2; ++mm)
; #pragma unroll
;                 for (int bj = 0; bj < 2; ++bj) xq[mm][bj] = *(const u32x4*)(xb + (size_t)(row0 + ai * 128 + (mh + mm) * 16) * D + c0 + bj * 128);
;             __builtin_amdgcn_sched_barrier(0);
; #pragma unroll
;             for (int mm = 0; mm < 2; ++mm)
; #pragma unroll
;                 for (int bj = 0; bj < 2; ++bj)
;                 { const u32x4 q = xq[mm][bj]; const f32x4 x0 = (f32x4){bf_lo(q.x), bf_hi(q.x), bf_lo(q.y), bf_hi(q.y)}, x1 = (f32x4){bf_lo(q.z), bf_hi(q.z), bf_lo(q.w), bf_hi(q.w)};
;                     *(u32x4*)(xb + (size_t)(row0 + ai * 128 + (mh + mm) * 16) * D + c0 + bj * 128) = pack8(x0 + gv[bj][0] * acc[ai][bj][mh + mm][0], x1 + gv[bj][1] * acc[ai][bj][mh + mm][1]); }
;             __builtin_amdgcn_sched_barrier(0);
;         }
.LBB0_48:
	s_lshr_b32 s14, s86, 5
	s_mulk_i32 s14, 0x3000
	s_ashr_i32 s15, s14, 31
	s_lshl_b64 s[14:15], s[14:15], 2
	v_lshl_or_b32 v154, s87, 8, v169
	s_add_u32 s14, s21, s14
	s_addc_u32 s15, s34, s15
	v_ashrrev_i32_e32 v155, 31, v154
	v_lshl_add_u32 v174, s86, 8, v160
	v_lshl_add_u64 v[132:133], v[154:155], 2, s[14:15]
	v_lshlrev_b64 v[154:155], 1, v[154:155]
	v_ashrrev_i32_e32 v175, 31, v174
	v_lshl_add_u64 v[156:157], s[6:7], 0, v[154:155]
	v_lshlrev_b64 v[158:159], 12, v[174:175]
	v_lshl_add_u64 v[178:179], v[156:157], 0, v[158:159]
	global_load_dwordx4 v[136:139], v[132:133], off offset:16
	global_load_dwordx4 v[140:143], v[132:133], off
	global_load_dwordx4 v[128:131], v[132:133], off offset:528
	s_nop 0
	global_load_dwordx4 v[132:135], v[132:133], off offset:512
	s_nop 0
	global_load_dwordx4 v[170:173], v[178:179], off
	global_load_dwordx4 v[182:185], v[178:179], off offset:256
	v_or_b32_e32 v178, 16, v174
	v_ashrrev_i32_e32 v179, 31, v178
	v_lshlrev_b64 v[178:179], 12, v[178:179]
	v_lshl_add_u64 v[180:181], v[156:157], 0, v[178:179]
	global_load_dwordx4 v[190:193], v[180:181], off
	global_load_dwordx4 v[194:197], v[180:181], off offset:256
	v_or_b32_e32 v200, 32, v174
	v_or_b32_e32 v208, 48, v174
	v_ashrrev_i32_e32 v201, 31, v200
	v_ashrrev_i32_e32 v209, 31, v208
	v_lshlrev_b64 v[226:227], 12, v[200:201]
	v_lshlrev_b64 v[228:229], 12, v[208:209]
	v_lshl_add_u64 v[204:205], v[156:157], 0, v[226:227]
	v_lshl_add_u64 v[222:223], v[156:157], 0, v[228:229]
	global_load_dwordx4 v[200:203], v[204:205], off
	s_nop 0
	global_load_dwordx4 v[204:207], v[204:205], off offset:256
	s_nop 0
	global_load_dwordx4 v[208:211], v[222:223], off
	s_nop 0
	global_load_dwordx4 v[222:225], v[222:223], off offset:256
	s_waitcnt vmcnt(4)
	v_lshlrev_b32_e32 v180, 16, v170
	v_and_b32_e32 v181, 0xffff0000, v170
	v_lshlrev_b32_e32 v170, 16, v171
	v_and_b32_e32 v171, 0xffff0000, v171
	v_lshlrev_b32_e32 v198, 16, v172
	v_and_b32_e32 v199, 0xffff0000, v172
	v_lshlrev_b32_e32 v172, 16, v173
	v_and_b32_e32 v173, 0xffff0000, v173
	v_pk_fma_f32 v[124:125], v[124:125], v[140:141], v[180:181]
	v_pk_fma_f32 v[126:127], v[126:127], v[142:143], v[170:171]
	v_pk_fma_f32 v[170:171], v[122:123], v[138:139], v[172:173]
	v_pk_fma_f32 v[122:123], v[120:121], v[136:137], v[198:199]
	v_cvt_pk_bf16_f32 v120, v124, v125
	v_lshl_add_u64 v[124:125], s[6:7], 0, v[158:159]
	v_cvt_pk_bf16_f32 v121, v126, v127
	v_cvt_pk_bf16_f32 v122, v122, v123
	v_cvt_pk_bf16_f32 v123, v170, v171
	v_lshl_add_u64 v[124:125], v[124:125], 0, v[154:155]
	global_store_dwordx4 v[124:125], v[120:123], off
	v_lshlrev_b32_e32 v126, 16, v184
	v_and_b32_e32 v127, 0xffff0000, v184
	v_lshlrev_b32_e32 v120, 16, v182
	v_and_b32_e32 v121, 0xffff0000, v182
	v_lshlrev_b32_e32 v122, 16, v183
	v_and_b32_e32 v123, 0xffff0000, v183
	v_lshlrev_b32_e32 v170, 16, v185
	v_and_b32_e32 v171, 0xffff0000, v185
	v_pk_fma_f32 v[118:119], v[118:119], v[134:135], v[122:123]
	v_pk_fma_f32 v[116:117], v[116:117], v[132:133], v[120:121]
	v_pk_fma_f32 v[120:121], v[114:115], v[130:131], v[170:171]
	v_pk_fma_f32 v[114:115], v[112:113], v[128:129], v[126:127]
	v_cvt_pk_bf16_f32 v112, v116, v117
	v_cvt_pk_bf16_f32 v113, v118, v119
	v_lshlrev_b32_e32 v116, 16, v192
	v_cvt_pk_bf16_f32 v114, v114, v115
	v_cvt_pk_bf16_f32 v115, v120, v121
	global_store_dwordx4 v[124:125], v[112:115], off offset:256
	v_and_b32_e32 v117, 0xffff0000, v192
	v_lshlrev_b32_e32 v118, 16, v193
	v_lshlrev_b32_e32 v112, 16, v190
	v_and_b32_e32 v113, 0xffff0000, v190
	v_and_b32_e32 v119, 0xffff0000, v193
	v_pk_fma_f32 v[108:109], v[108:109], v[140:141], v[112:113]
	v_lshlrev_b32_e32 v114, 16, v191
	v_and_b32_e32 v115, 0xffff0000, v191
	v_pk_fma_f32 v[112:113], v[106:107], v[138:139], v[118:119]
	v_pk_fma_f32 v[106:107], v[104:105], v[136:137], v[116:117]
	v_cvt_pk_bf16_f32 v104, v108, v109
	v_lshl_add_u64 v[108:109], s[6:7], 0, v[178:179]
	v_pk_fma_f32 v[110:111], v[110:111], v[142:143], v[114:115]
	v_lshl_add_u64 v[108:109], v[108:109], 0, v[154:155]
	v_cvt_pk_bf16_f32 v105, v110, v111
	v_cvt_pk_bf16_f32 v106, v106, v107
	v_cvt_pk_bf16_f32 v107, v112, v113
	global_store_dwordx4 v[108:109], v[104:107], off
	v_lshlrev_b32_e32 v110, 16, v196
	v_and_b32_e32 v111, 0xffff0000, v196
	v_lshlrev_b32_e32 v104, 16, v194
	v_and_b32_e32 v105, 0xffff0000, v194
	v_lshlrev_b32_e32 v112, 16, v197
	v_and_b32_e32 v113, 0xffff0000, v197
	v_lshlrev_b32_e32 v106, 16, v195
	v_and_b32_e32 v107, 0xffff0000, v195
	v_pk_fma_f32 v[100:101], v[100:101], v[132:133], v[104:105]
	v_pk_fma_f32 v[104:105], v[98:99], v[130:131], v[112:113]
	v_pk_fma_f32 v[98:99], v[96:97], v[128:129], v[110:111]
	v_pk_fma_f32 v[102:103], v[102:103], v[134:135], v[106:107]
	v_cvt_pk_bf16_f32 v96, v100, v101
	s_nop 0
	v_cvt_pk_bf16_f32 v97, v102, v103
	v_cvt_pk_bf16_f32 v98, v98, v99
	v_cvt_pk_bf16_f32 v99, v104, v105
	global_store_dwordx4 v[108:109], v[96:99], off offset:256
	v_lshl_add_u64 v[242:243], v[158:159], 0, s[54:55]
	v_lshl_add_u64 v[250:251], v[158:159], 0, s[56:57]
	v_lshl_add_u64 v[234:235], v[156:157], 0, v[242:243]
	v_lshl_add_u64 v[246:247], v[156:157], 0, v[250:251]
	global_load_dwordx4 v[230:233], v[234:235], off
	s_nop 0
	global_load_dwordx4 v[234:237], v[234:235], off offset:256
	s_nop 0
	global_load_dwordx4 v[238:241], v[246:247], off
	s_nop 0
	global_load_dwordx4 v[246:249], v[246:247], off offset:256
	s_waitcnt vmcnt(8)
; __device__ __forceinline__ float bf_lo(unsigned u) { return __uint_as_float(u << 16); }
; __device__ __forceinline__ float bf_hi(unsigned u) { return __uint_as_float(u & 0xffff0000u); }
; __device__ __forceinline__ u32x4 pack8(const f32x4 a, const f32x4 b) { u32x4 w; w.x = cvt_pk_bf16(a[0], a[1]); w.y = cvt_pk_bf16(a[2], a[3]); w.z = cvt_pk_bf16(b[0], b[1]); w.w = cvt_pk_bf16(b[2], b[3]); return w; }
;     __device__ __forceinline__ bool operator()(f32x4 (&acc)[2][2][4][2], const Unit& u, int wr, int wc, int fr, int fq) const {
;     ...
;         for (int b4 = 0; b4 < 4; ++b4) {
;             const int ai = b4 >> 1, mh = (b4 & 1) * 2;
;             u32x4 xq[2][2];
; #pragma unroll
;             for (int mm = 0; mm < 2; ++mm)
; #pragma unroll
;                 for (int bj = 0; bj < 2; ++bj) xq[mm][bj] = *(const u32x4*)(xb + (size_t)(row0 + ai * 128 + (mh + mm) * 16) * D + c0 + bj * 128);
;             __builtin_amdgcn_sched_barrier(0);
; #pragma unroll
;             for (int mm = 0; mm < 2; ++mm)
; #pragma unroll
;                 for (int bj = 0; bj < 2; ++bj)
;                 { const u32x4 q = xq[mm][bj]; const f32x4 x0 = (f32x4){bf_lo(q.x), bf_hi(q.x), bf_lo(q.y), bf_hi(q.y)}, x1 = (f32x4){bf_lo(q.z), bf_hi(q.z), bf_lo(q.w), bf_hi(q.w)};
;                     *(u32x4*)(xb + (size_t)(row0 + ai * 128 + (mh + mm) * 16) * D + c0 + bj * 128) = pack8(x0 + gv[bj][0] * acc[ai][bj][mh + mm][0], x1 + gv[bj][1] * acc[ai][bj][mh + mm][1]); }
;             __builtin_amdgcn_sched_barrier(0);
	v_lshlrev_b32_e32 v116, 16, v200
	v_and_b32_e32 v117, 0xffff0000, v200
	v_lshlrev_b32_e32 v200, 16, v201
	v_and_b32_e32 v201, 0xffff0000, v201
	v_lshlrev_b32_e32 v118, 16, v202
	v_and_b32_e32 v119, 0xffff0000, v202
	v_lshlrev_b32_e32 v202, 16, v203
	v_and_b32_e32 v203, 0xffff0000, v203
	v_pk_fma_f32 v[92:93], v[92:93], v[140:141], v[116:117]
	v_pk_fma_f32 v[94:95], v[94:95], v[142:143], v[200:201]
	v_pk_fma_f32 v[200:201], v[90:91], v[138:139], v[202:203]
	v_pk_fma_f32 v[90:91], v[88:89], v[136:137], v[118:119]
	v_cvt_pk_bf16_f32 v88, v92, v93
	v_lshl_add_u64 v[92:93], s[6:7], 0, v[226:227]
	v_cvt_pk_bf16_f32 v89, v94, v95
	v_cvt_pk_bf16_f32 v90, v90, v91
	v_cvt_pk_bf16_f32 v91, v200, v201
	v_lshl_add_u64 v[92:93], v[92:93], 0, v[154:155]
	global_store_dwordx4 v[92:93], v[88:91], off
	v_lshlrev_b32_e32 v94, 16, v206
	v_and_b32_e32 v95, 0xffff0000, v206
	v_lshlrev_b32_e32 v88, 16, v204
	v_and_b32_e32 v89, 0xffff0000, v204
	v_lshlrev_b32_e32 v90, 16, v205
	v_and_b32_e32 v91, 0xffff0000, v205
	v_lshlrev_b32_e32 v200, 16, v207
	v_and_b32_e32 v201, 0xffff0000, v207
	v_pk_fma_f32 v[86:87], v[86:87], v[134:135], v[90:91]
	v_pk_fma_f32 v[84:85], v[84:85], v[132:133], v[88:89]
	v_pk_fma_f32 v[88:89], v[82:83], v[130:131], v[200:201]
	v_pk_fma_f32 v[82:83], v[80:81], v[128:129], v[94:95]
	v_cvt_pk_bf16_f32 v80, v84, v85
	v_cvt_pk_bf16_f32 v81, v86, v87
	v_lshlrev_b32_e32 v84, 16, v210
	v_cvt_pk_bf16_f32 v82, v82, v83
	v_cvt_pk_bf16_f32 v83, v88, v89
	global_store_dwordx4 v[92:93], v[80:83], off offset:256
	v_and_b32_e32 v85, 0xffff0000, v210
	v_lshlrev_b32_e32 v86, 16, v211
	v_lshlrev_b32_e32 v80, 16, v208
	v_and_b32_e32 v81, 0xffff0000, v208
	v_and_b32_e32 v87, 0xffff0000, v211
	v_pk_fma_f32 v[76:77], v[76:77], v[140:141], v[80:81]
	v_lshlrev_b32_e32 v82, 16, v209
	v_and_b32_e32 v83, 0xffff0000, v209
	v_pk_fma_f32 v[80:81], v[74:75], v[138:139], v[86:87]
	v_pk_fma_f32 v[74:75], v[72:73], v[136:137], v[84:85]
	v_cvt_pk_bf16_f32 v72, v76, v77
	v_lshl_add_u64 v[76:77], s[6:7], 0, v[228:229]
	v_pk_fma_f32 v[78:79], v[78:79], v[142:143], v[82:83]
	v_lshl_add_u64 v[76:77], v[76:77], 0, v[154:155]
	v_cvt_pk_bf16_f32 v73, v78, v79
	v_cvt_pk_bf16_f32 v74, v74, v75
	v_cvt_pk_bf16_f32 v75, v80, v81
	global_store_dwordx4 v[76:77], v[72:75], off
	v_lshlrev_b32_e32 v78, 16, v224
	v_and_b32_e32 v79, 0xffff0000, v224
	v_lshlrev_b32_e32 v72, 16, v222
	v_and_b32_e32 v73, 0xffff0000, v222
	v_lshlrev_b32_e32 v80, 16, v225
	v_and_b32_e32 v81, 0xffff0000, v225
	v_lshlrev_b32_e32 v74, 16, v223
	v_and_b32_e32 v75, 0xffff0000, v223
	v_pk_fma_f32 v[68:69], v[68:69], v[132:133], v[72:73]
	v_pk_fma_f32 v[72:73], v[66:67], v[130:131], v[80:81]
	v_pk_fma_f32 v[66:67], v[64:65], v[128:129], v[78:79]
	v_pk_fma_f32 v[70:71], v[70:71], v[134:135], v[74:75]
	v_cvt_pk_bf16_f32 v64, v68, v69
	s_nop 0
	v_cvt_pk_bf16_f32 v65, v70, v71
	v_cvt_pk_bf16_f32 v66, v66, v67
	v_cvt_pk_bf16_f32 v67, v72, v73
	global_store_dwordx4 v[76:77], v[64:67], off offset:256
	s_mov_b64 s[14:15], 0xb0000
	v_lshl_add_u64 v[226:227], v[158:159], 0, s[58:59]
	v_lshl_add_u64 v[228:229], v[158:159], 0, s[14:15]
	v_lshl_add_u64 v[204:205], v[156:157], 0, v[226:227]
	v_lshl_add_u64 v[222:223], v[156:157], 0, v[228:229]
	global_load_dwordx4 v[200:203], v[204:205], off
	s_nop 0
	global_load_dwordx4 v[204:207], v[204:205], off offset:256
	s_nop 0
	global_load_dwordx4 v[208:211], v[222:223], off
	s_nop 0
	global_load_dwordx4 v[222:225], v[222:223], off offset:256
	s_waitcnt vmcnt(8)
; __device__ __forceinline__ float bf_lo(unsigned u) { return __uint_as_float(u << 16); }
; __device__ __forceinline__ float bf_hi(unsigned u) { return __uint_as_float(u & 0xffff0000u); }
; __device__ __forceinline__ u32x4 pack8(const f32x4 a, const f32x4 b) { u32x4 w; w.x = cvt_pk_bf16(a[0], a[1]); w.y = cvt_pk_bf16(a[2], a[3]); w.z = cvt_pk_bf16(b[0], b[1]); w.w = cvt_pk_bf16(b[2], b[3]); return w; }
; template <int NT, class Epi>
; __device__ __forceinline__ void gemm_phase(LAS unsigned char* lds, const int K, const Sched& S, const Epi& E, const int wave_s) {
;     ...
;         const bool keep = E(acc, cur, wr, wc, fr, fq);
;         __builtin_amdgcn_s_waitcnt(0x0F70);
;         if (!has_next) break;
;     __device__ __forceinline__ bool operator()(f32x4 (&acc)[2][2][4][2], const Unit& u, int wr, int wc, int fr, int fq) const {
;     ...
;         for (int b4 = 0; b4 < 4; ++b4) {
;             const int ai = b4 >> 1, mh = (b4 & 1) * 2;
;             u32x4 xq[2][2];
; #pragma unroll
;             for (int mm = 0; mm < 2; ++mm)
; #pragma unroll
;                 for (int bj = 0; bj < 2; ++bj) xq[mm][bj] = *(const u32x4*)(xb + (size_t)(row0 + ai * 128 + (mh + mm) * 16) * D + c0 + bj * 128);
;             __builtin_amdgcn_sched_barrier(0);
; #pragma unroll
;             for (int mm = 0; mm < 2; ++mm)
; #pragma unroll
;                 for (int bj = 0; bj < 2; ++bj)
;                 { const u32x4 q = xq[mm][bj]; const f32x4 x0 = (f32x4){bf_lo(q.x), bf_hi(q.x), bf_lo(q.y), bf_hi(q.y)}, x1 = (f32x4){bf_lo(q.z), bf_hi(q.z), bf_lo(q.w), bf_hi(q.w)};
;                     *(u32x4*)(xb + (size_t)(row0 + ai * 128 + (mh + mm) * 16) * D + c0 + bj * 128) = pack8(x0 + gv[bj][0] * acc[ai][bj][mh + mm][0], x1 + gv[bj][1] * acc[ai][bj][mh + mm][1]); }
;             __builtin_amdgcn_sched_barrier(0);
;         }
	v_lshlrev_b32_e32 v84, 16, v230
	v_and_b32_e32 v85, 0xffff0000, v230
	v_lshlrev_b32_e32 v230, 16, v231
	v_and_b32_e32 v231, 0xffff0000, v231
	v_lshlrev_b32_e32 v86, 16, v232
	v_and_b32_e32 v87, 0xffff0000, v232
	v_lshlrev_b32_e32 v232, 16, v233
	v_and_b32_e32 v233, 0xffff0000, v233
	v_pk_fma_f32 v[60:61], v[60:61], v[140:141], v[84:85]
	v_pk_fma_f32 v[62:63], v[62:63], v[142:143], v[230:231]
	v_pk_fma_f32 v[230:231], v[58:59], v[138:139], v[232:233]
	v_pk_fma_f32 v[58:59], v[56:57], v[136:137], v[86:87]
	v_cvt_pk_bf16_f32 v56, v60, v61
	v_lshl_add_u64 v[60:61], s[6:7], 0, v[242:243]
	v_cvt_pk_bf16_f32 v57, v62, v63
	v_cvt_pk_bf16_f32 v58, v58, v59
	v_cvt_pk_bf16_f32 v59, v230, v231
	v_lshl_add_u64 v[60:61], v[60:61], 0, v[154:155]
	global_store_dwordx4 v[60:61], v[56:59], off
	v_lshlrev_b32_e32 v62, 16, v236
	v_and_b32_e32 v63, 0xffff0000, v236
	v_lshlrev_b32_e32 v56, 16, v234
	v_and_b32_e32 v57, 0xffff0000, v234
	v_lshlrev_b32_e32 v58, 16, v235
	v_and_b32_e32 v59, 0xffff0000, v235
	v_lshlrev_b32_e32 v230, 16, v237
	v_and_b32_e32 v231, 0xffff0000, v237
	v_pk_fma_f32 v[54:55], v[54:55], v[134:135], v[58:59]
	v_pk_fma_f32 v[52:53], v[52:53], v[132:133], v[56:57]
	v_pk_fma_f32 v[56:57], v[50:51], v[130:131], v[230:231]
	v_pk_fma_f32 v[50:51], v[48:49], v[128:129], v[62:63]
	v_cvt_pk_bf16_f32 v48, v52, v53
	v_cvt_pk_bf16_f32 v49, v54, v55
	v_lshlrev_b32_e32 v52, 16, v240
	v_cvt_pk_bf16_f32 v50, v50, v51
	v_cvt_pk_bf16_f32 v51, v56, v57
	global_store_dwordx4 v[60:61], v[48:51], off offset:256
	v_and_b32_e32 v53, 0xffff0000, v240
	v_lshlrev_b32_e32 v54, 16, v241
	v_lshlrev_b32_e32 v48, 16, v238
	v_and_b32_e32 v49, 0xffff0000, v238
	v_and_b32_e32 v55, 0xffff0000, v241
	v_pk_fma_f32 v[44:45], v[44:45], v[140:141], v[48:49]
	v_lshlrev_b32_e32 v50, 16, v239
	v_and_b32_e32 v51, 0xffff0000, v239
	v_pk_fma_f32 v[48:49], v[42:43], v[138:139], v[54:55]
	v_pk_fma_f32 v[42:43], v[40:41], v[136:137], v[52:53]
	v_cvt_pk_bf16_f32 v40, v44, v45
	v_lshl_add_u64 v[44:45], s[6:7], 0, v[250:251]
	v_pk_fma_f32 v[46:47], v[46:47], v[142:143], v[50:51]
	v_lshl_add_u64 v[44:45], v[44:45], 0, v[154:155]
	v_cvt_pk_bf16_f32 v41, v46, v47
	v_cvt_pk_bf16_f32 v42, v42, v43
	v_cvt_pk_bf16_f32 v43, v48, v49
	global_store_dwordx4 v[44:45], v[40:43], off
	v_lshlrev_b32_e32 v46, 16, v248
	v_and_b32_e32 v47, 0xffff0000, v248
	v_lshlrev_b32_e32 v40, 16, v246
	v_and_b32_e32 v41, 0xffff0000, v246
	v_lshlrev_b32_e32 v48, 16, v249
	v_and_b32_e32 v49, 0xffff0000, v249
	v_lshlrev_b32_e32 v42, 16, v247
	v_and_b32_e32 v43, 0xffff0000, v247
	v_pk_fma_f32 v[36:37], v[36:37], v[132:133], v[40:41]
	v_pk_fma_f32 v[40:41], v[34:35], v[130:131], v[48:49]
	v_pk_fma_f32 v[34:35], v[32:33], v[128:129], v[46:47]
	v_pk_fma_f32 v[38:39], v[38:39], v[134:135], v[42:43]
	v_cvt_pk_bf16_f32 v32, v36, v37
	s_nop 0
	v_cvt_pk_bf16_f32 v33, v38, v39
	v_cvt_pk_bf16_f32 v34, v34, v35
	v_cvt_pk_bf16_f32 v35, v40, v41
	global_store_dwordx4 v[44:45], v[32:35], off offset:256
	s_waitcnt vmcnt(4)
	v_lshlrev_b32_e32 v52, 16, v200
	v_and_b32_e32 v53, 0xffff0000, v200
	v_lshlrev_b32_e32 v200, 16, v201
	v_and_b32_e32 v201, 0xffff0000, v201
	v_lshlrev_b32_e32 v54, 16, v202
	v_and_b32_e32 v55, 0xffff0000, v202
	v_lshlrev_b32_e32 v202, 16, v203
	v_and_b32_e32 v203, 0xffff0000, v203
	v_pk_fma_f32 v[28:29], v[28:29], v[140:141], v[52:53]
	v_pk_fma_f32 v[30:31], v[30:31], v[142:143], v[200:201]
	v_pk_fma_f32 v[200:201], v[26:27], v[138:139], v[202:203]
	v_pk_fma_f32 v[26:27], v[24:25], v[136:137], v[54:55]
	v_cvt_pk_bf16_f32 v24, v28, v29
	v_lshl_add_u64 v[28:29], s[6:7], 0, v[226:227]
	v_cvt_pk_bf16_f32 v25, v30, v31
	v_cvt_pk_bf16_f32 v26, v26, v27
	v_cvt_pk_bf16_f32 v27, v200, v201
	v_lshl_add_u64 v[28:29], v[28:29], 0, v[154:155]
	global_store_dwordx4 v[28:29], v[24:27], off
	v_lshlrev_b32_e32 v30, 16, v206
	v_and_b32_e32 v31, 0xffff0000, v206
	v_lshlrev_b32_e32 v24, 16, v204
	v_and_b32_e32 v25, 0xffff0000, v204
	v_lshlrev_b32_e32 v26, 16, v205
	v_and_b32_e32 v27, 0xffff0000, v205
	v_lshlrev_b32_e32 v200, 16, v207
	v_and_b32_e32 v201, 0xffff0000, v207
	v_pk_fma_f32 v[22:23], v[22:23], v[134:135], v[26:27]
	v_pk_fma_f32 v[20:21], v[20:21], v[132:133], v[24:25]
	v_pk_fma_f32 v[24:25], v[18:19], v[130:131], v[200:201]
	v_pk_fma_f32 v[18:19], v[16:17], v[128:129], v[30:31]
	v_cvt_pk_bf16_f32 v16, v20, v21
	v_cvt_pk_bf16_f32 v17, v22, v23
	v_lshlrev_b32_e32 v20, 16, v210
	v_cvt_pk_bf16_f32 v18, v18, v19
	v_cvt_pk_bf16_f32 v19, v24, v25
	global_store_dwordx4 v[28:29], v[16:19], off offset:256
	v_and_b32_e32 v21, 0xffff0000, v210
	v_lshlrev_b32_e32 v22, 16, v211
	v_lshlrev_b32_e32 v16, 16, v208
	v_and_b32_e32 v17, 0xffff0000, v208
	v_and_b32_e32 v23, 0xffff0000, v211
	v_pk_fma_f32 v[12:13], v[12:13], v[140:141], v[16:17]
	v_lshlrev_b32_e32 v18, 16, v209
	v_and_b32_e32 v19, 0xffff0000, v209
	v_pk_fma_f32 v[16:17], v[10:11], v[138:139], v[22:23]
	v_pk_fma_f32 v[10:11], v[8:9], v[136:137], v[20:21]
	v_cvt_pk_bf16_f32 v8, v12, v13
	v_lshl_add_u64 v[12:13], s[6:7], 0, v[228:229]
	v_pk_fma_f32 v[14:15], v[14:15], v[142:143], v[18:19]
	v_lshl_add_u64 v[12:13], v[12:13], 0, v[154:155]
	v_cvt_pk_bf16_f32 v9, v14, v15
	v_cvt_pk_bf16_f32 v10, v10, v11
	v_cvt_pk_bf16_f32 v11, v16, v17
	global_store_dwordx4 v[12:13], v[8:11], off
	v_lshlrev_b32_e32 v14, 16, v224
	v_and_b32_e32 v15, 0xffff0000, v224
	v_lshlrev_b32_e32 v8, 16, v222
	v_and_b32_e32 v9, 0xffff0000, v222
	v_lshlrev_b32_e32 v16, 16, v225
	v_and_b32_e32 v17, 0xffff0000, v225
	v_lshlrev_b32_e32 v10, 16, v223
	v_and_b32_e32 v11, 0xffff0000, v223
	v_pk_fma_f32 v[4:5], v[4:5], v[132:133], v[8:9]
	v_pk_fma_f32 v[8:9], v[2:3], v[130:131], v[16:17]
	v_pk_fma_f32 v[2:3], v[0:1], v[128:129], v[14:15]
	v_pk_fma_f32 v[6:7], v[6:7], v[134:135], v[10:11]
	v_cvt_pk_bf16_f32 v0, v4, v5
	s_nop 0
	v_cvt_pk_bf16_f32 v1, v6, v7
	v_cvt_pk_bf16_f32 v2, v2, v3
	v_cvt_pk_bf16_f32 v3, v8, v9
	global_store_dwordx4 v[12:13], v[0:3], off offset:256
	v_readlane_b32 s90, v255, 36
	s_and_b64 vcc, exec, s[38:39]
	s_mov_b64 s[18:19], -1
	v_readlane_b32 s91, v255, 37
	s_mov_b64 s[38:39], 0x800
	s_waitcnt vmcnt(0)
	s_cbranch_vccnz .LBB0_33
	s_andn2_b64 vcc, exec, s[8:9]
	s_cbranch_vccnz .LBB0_32
	s_barrier
	s_branch .LBB0_32

; __device__ __forceinline__ float bf_lo(unsigned u) { return __uint_as_float(u << 16); }
; __device__ __forceinline__ float bf_hi(unsigned u) { return __uint_as_float(u & 0xffff0000u); }
; __device__ __forceinline__ u32x4 pack8(const f32x4 a, const f32x4 b) { u32x4 w; w.x = cvt_pk_bf16(a[0], a[1]); w.y = cvt_pk_bf16(a[2], a[3]); w.z = cvt_pk_bf16(b[0], b[1]); w.w = cvt_pk_bf16(b[2], b[3]); return w; }
;     __device__ __forceinline__ bool operator()(f32x4 (&acc)[2][2][4][2], const Unit& u, int wr, int wc, int fr, int fq) const {
;     ...
;         const int vec = u.pm >> 5;
;         const int row0 = u.pm * 256 + wr * 64 + fr, c0 = u.pn * 256 + wc * 32 + fq * 8;
;         const float* gp = gate + vec * 12288 + c0;
;         f32x4 gv[2][2];
; #pragma unroll
;         for (int bj = 0; bj < 2; ++bj) { gv[bj][0] = *(const f32x4*)(gp + bj * 128); gv[bj][1] = *(const f32x4*)(gp + bj * 128 + 4); }
; #pragma unroll
;         for (int b4 = 0; b4 < 4; ++b4) {
;             const int ai = b4 >> 1, mh = (b4 & 1) * 2;
;             u32x4 xq[2][2];
; #pragma unroll
;             for (int mm = 0; mm < 2; ++mm)
; #pragma unroll
;                 for (int bj = 0; bj < 2; ++bj) xq[mm][bj] = *(const u32x4*)(xb + (size_t)(row0 + ai * 128 + (mh + mm) * 16) * D + c0 + bj * 128);
;             __builtin_amdgcn_sched_barrier(0);
; #pragma unroll
;             for (int mm = 0; mm < 2; ++mm)
; #pragma unroll
;                 for (int bj = 0; bj < 2; ++bj)
;                 { const u32x4 q = xq[mm][bj]; const f32x4 x0 = (f32x4){bf_lo(q.x), bf_hi(q.x), bf_lo(q.y), bf_hi(q.y)}, x1 = (f32x4){bf_lo(q.z), bf_hi(q.z), bf_lo(q.w), bf_hi(q.w)};
;                     *(u32x4*)(xb + (size_t)(row0 + ai * 128 + (mh + mm) * 16) * D + c0 + bj * 128) = pack8(x0 + gv[bj][0] * acc[ai][bj][mh + mm][0], x1 + gv[bj][1] * acc[ai][bj][mh + mm][1]); }
;             __builtin_amdgcn_sched_barrier(0);
;         }
.LBB0_120:
	s_lshr_b32 s13, s85, 5
	s_mul_i32 s14, s13, 0x3000
	s_ashr_i32 s15, s14, 31
	s_lshl_b64 s[14:15], s[14:15], 2
	v_lshl_or_b32 v154, s86, 8, v169
	s_add_u32 s14, s2, s14
	s_addc_u32 s15, s0, s15
	v_ashrrev_i32_e32 v155, 31, v154
	v_lshl_add_u32 v174, s85, 8, v160
	v_lshl_add_u64 v[132:133], v[154:155], 2, s[14:15]
	v_lshlrev_b64 v[154:155], 1, v[154:155]
	v_ashrrev_i32_e32 v175, 31, v174
	v_lshl_add_u64 v[156:157], s[6:7], 0, v[154:155]
	v_lshlrev_b64 v[158:159], 12, v[174:175]
	v_lshl_add_u64 v[178:179], v[156:157], 0, v[158:159]
	global_load_dwordx4 v[136:139], v[132:133], off offset:16
	global_load_dwordx4 v[140:143], v[132:133], off
	global_load_dwordx4 v[128:131], v[132:133], off offset:528
	s_nop 0
	global_load_dwordx4 v[132:135], v[132:133], off offset:512
	s_nop 0
	global_load_dwordx4 v[170:173], v[178:179], off
	global_load_dwordx4 v[182:185], v[178:179], off offset:256
	v_or_b32_e32 v178, 16, v174
	v_ashrrev_i32_e32 v179, 31, v178
	v_lshlrev_b64 v[178:179], 12, v[178:179]
	v_lshl_add_u64 v[180:181], v[156:157], 0, v[178:179]
	global_load_dwordx4 v[190:193], v[180:181], off
	global_load_dwordx4 v[194:197], v[180:181], off offset:256
	v_or_b32_e32 v200, 32, v174
	v_or_b32_e32 v208, 48, v174
	v_ashrrev_i32_e32 v201, 31, v200
	v_ashrrev_i32_e32 v209, 31, v208
	v_lshlrev_b64 v[226:227], 12, v[200:201]
	v_lshlrev_b64 v[228:229], 12, v[208:209]
	v_lshl_add_u64 v[204:205], v[156:157], 0, v[226:227]
	v_lshl_add_u64 v[222:223], v[156:157], 0, v[228:229]
	global_load_dwordx4 v[200:203], v[204:205], off
	s_nop 0
	global_load_dwordx4 v[204:207], v[204:205], off offset:256
	s_nop 0
	global_load_dwordx4 v[208:211], v[222:223], off
	s_nop 0
	global_load_dwordx4 v[222:225], v[222:223], off offset:256
	s_waitcnt vmcnt(4)
	v_lshlrev_b32_e32 v180, 16, v170
	v_and_b32_e32 v181, 0xffff0000, v170
	v_lshlrev_b32_e32 v170, 16, v171
	v_and_b32_e32 v171, 0xffff0000, v171
	v_lshlrev_b32_e32 v198, 16, v172
	v_and_b32_e32 v199, 0xffff0000, v172
	v_lshlrev_b32_e32 v172, 16, v173
	v_and_b32_e32 v173, 0xffff0000, v173
	v_pk_fma_f32 v[124:125], v[124:125], v[140:141], v[180:181]
	v_pk_fma_f32 v[126:127], v[126:127], v[142:143], v[170:171]
	v_pk_fma_f32 v[170:171], v[122:123], v[138:139], v[172:173]
	v_pk_fma_f32 v[122:123], v[120:121], v[136:137], v[198:199]
	v_cvt_pk_bf16_f32 v120, v124, v125
	v_lshl_add_u64 v[124:125], s[6:7], 0, v[158:159]
	v_cvt_pk_bf16_f32 v121, v126, v127
	v_cvt_pk_bf16_f32 v122, v122, v123
	v_cvt_pk_bf16_f32 v123, v170, v171
	v_lshl_add_u64 v[124:125], v[124:125], 0, v[154:155]
	global_store_dwordx4 v[124:125], v[120:123], off
	v_lshlrev_b32_e32 v126, 16, v184
	v_and_b32_e32 v127, 0xffff0000, v184
	v_lshlrev_b32_e32 v120, 16, v182
	v_and_b32_e32 v121, 0xffff0000, v182
	v_lshlrev_b32_e32 v122, 16, v183
	v_and_b32_e32 v123, 0xffff0000, v183
	v_lshlrev_b32_e32 v170, 16, v185
	v_and_b32_e32 v171, 0xffff0000, v185
	v_pk_fma_f32 v[118:119], v[118:119], v[134:135], v[122:123]
	v_pk_fma_f32 v[116:117], v[116:117], v[132:133], v[120:121]
	v_pk_fma_f32 v[120:121], v[114:115], v[130:131], v[170:171]
	v_pk_fma_f32 v[114:115], v[112:113], v[128:129], v[126:127]
	v_cvt_pk_bf16_f32 v112, v116, v117
	v_cvt_pk_bf16_f32 v113, v118, v119
	v_lshlrev_b32_e32 v116, 16, v192
	v_cvt_pk_bf16_f32 v114, v114, v115
	v_cvt_pk_bf16_f32 v115, v120, v121
	global_store_dwordx4 v[124:125], v[112:115], off offset:256
	v_and_b32_e32 v117, 0xffff0000, v192
	v_lshlrev_b32_e32 v118, 16, v193
	v_lshlrev_b32_e32 v112, 16, v190
	v_and_b32_e32 v113, 0xffff0000, v190
	v_and_b32_e32 v119, 0xffff0000, v193
	v_pk_fma_f32 v[108:109], v[108:109], v[140:141], v[112:113]
	v_lshlrev_b32_e32 v114, 16, v191
	v_and_b32_e32 v115, 0xffff0000, v191
	v_pk_fma_f32 v[112:113], v[106:107], v[138:139], v[118:119]
	v_pk_fma_f32 v[106:107], v[104:105], v[136:137], v[116:117]
	v_cvt_pk_bf16_f32 v104, v108, v109
	v_lshl_add_u64 v[108:109], s[6:7], 0, v[178:179]
	v_pk_fma_f32 v[110:111], v[110:111], v[142:143], v[114:115]
	v_lshl_add_u64 v[108:109], v[108:109], 0, v[154:155]
	v_cvt_pk_bf16_f32 v105, v110, v111
	v_cvt_pk_bf16_f32 v106, v106, v107
	v_cvt_pk_bf16_f32 v107, v112, v113
	global_store_dwordx4 v[108:109], v[104:107], off
	v_lshlrev_b32_e32 v110, 16, v196
	v_and_b32_e32 v111, 0xffff0000, v196
	v_lshlrev_b32_e32 v104, 16, v194
	v_and_b32_e32 v105, 0xffff0000, v194
	v_lshlrev_b32_e32 v112, 16, v197
	v_and_b32_e32 v113, 0xffff0000, v197
	v_lshlrev_b32_e32 v106, 16, v195
	v_and_b32_e32 v107, 0xffff0000, v195
	v_pk_fma_f32 v[100:101], v[100:101], v[132:133], v[104:105]
	v_pk_fma_f32 v[104:105], v[98:99], v[130:131], v[112:113]
	v_pk_fma_f32 v[98:99], v[96:97], v[128:129], v[110:111]
	v_pk_fma_f32 v[102:103], v[102:103], v[134:135], v[106:107]
	v_cvt_pk_bf16_f32 v96, v100, v101
	s_nop 0
	v_cvt_pk_bf16_f32 v97, v102, v103
	v_cvt_pk_bf16_f32 v98, v98, v99
	v_cvt_pk_bf16_f32 v99, v104, v105
	global_store_dwordx4 v[108:109], v[96:99], off offset:256
	v_lshl_add_u64 v[242:243], v[158:159], 0, s[54:55]
	v_lshl_add_u64 v[250:251], v[158:159], 0, s[56:57]
	v_lshl_add_u64 v[234:235], v[156:157], 0, v[242:243]
	v_lshl_add_u64 v[246:247], v[156:157], 0, v[250:251]
	global_load_dwordx4 v[230:233], v[234:235], off
	s_nop 0
	global_load_dwordx4 v[234:237], v[234:235], off offset:256
	s_nop 0
	global_load_dwordx4 v[238:241], v[246:247], off
	s_nop 0
	global_load_dwordx4 v[246:249], v[246:247], off offset:256
	s_waitcnt vmcnt(8)
; __device__ __forceinline__ float bf_lo(unsigned u) { return __uint_as_float(u << 16); }
; __device__ __forceinline__ float bf_hi(unsigned u) { return __uint_as_float(u & 0xffff0000u); }
; __device__ __forceinline__ u32x4 pack8(const f32x4 a, const f32x4 b) { u32x4 w; w.x = cvt_pk_bf16(a[0], a[1]); w.y = cvt_pk_bf16(a[2], a[3]); w.z = cvt_pk_bf16(b[0], b[1]); w.w = cvt_pk_bf16(b[2], b[3]); return w; }
;     __device__ __forceinline__ bool operator()(f32x4 (&acc)[2][2][4][2], const Unit& u, int wr, int wc, int fr, int fq) const {
;     ...
;         for (int b4 = 0; b4 < 4; ++b4) {
;             const int ai = b4 >> 1, mh = (b4 & 1) * 2;
;             u32x4 xq[2][2];
; #pragma unroll
;             for (int mm = 0; mm < 2; ++mm)
; #pragma unroll
;                 for (int bj = 0; bj < 2; ++bj) xq[mm][bj] = *(const u32x4*)(xb + (size_t)(row0 + ai * 128 + (mh + mm) * 16) * D + c0 + bj * 128);
;             __builtin_amdgcn_sched_barrier(0);
; #pragma unroll
;             for (int mm = 0; mm < 2; ++mm)
; #pragma unroll
;                 for (int bj = 0; bj < 2; ++bj)
;                 { const u32x4 q = xq[mm][bj]; const f32x4 x0 = (f32x4){bf_lo(q.x), bf_hi(q.x), bf_lo(q.y), bf_hi(q.y)}, x1 = (f32x4){bf_lo(q.z), bf_hi(q.z), bf_lo(q.w), bf_hi(q.w)};
;                     *(u32x4*)(xb + (size_t)(row0 + ai * 128 + (mh + mm) * 16) * D + c0 + bj * 128) = pack8(x0 + gv[bj][0] * acc[ai][bj][mh + mm][0], x1 + gv[bj][1] * acc[ai][bj][mh + mm][1]); }
;             __builtin_amdgcn_sched_barrier(0);
	v_lshlrev_b32_e32 v116, 16, v200
	v_and_b32_e32 v117, 0xffff0000, v200
	v_lshlrev_b32_e32 v200, 16, v201
	v_and_b32_e32 v201, 0xffff0000, v201
	v_lshlrev_b32_e32 v118, 16, v202
	v_and_b32_e32 v119, 0xffff0000, v202
	v_lshlrev_b32_e32 v202, 16, v203
	v_and_b32_e32 v203, 0xffff0000, v203
	v_pk_fma_f32 v[92:93], v[92:93], v[140:141], v[116:117]
	v_pk_fma_f32 v[94:95], v[94:95], v[142:143], v[200:201]
	v_pk_fma_f32 v[200:201], v[90:91], v[138:139], v[202:203]
	v_pk_fma_f32 v[90:91], v[88:89], v[136:137], v[118:119]
	v_cvt_pk_bf16_f32 v88, v92, v93
	v_lshl_add_u64 v[92:93], s[6:7], 0, v[226:227]
	v_cvt_pk_bf16_f32 v89, v94, v95
	v_cvt_pk_bf16_f32 v90, v90, v91
	v_cvt_pk_bf16_f32 v91, v200, v201
	v_lshl_add_u64 v[92:93], v[92:93], 0, v[154:155]
	global_store_dwordx4 v[92:93], v[88:91], off
	v_lshlrev_b32_e32 v94, 16, v206
	v_and_b32_e32 v95, 0xffff0000, v206
	v_lshlrev_b32_e32 v88, 16, v204
	v_and_b32_e32 v89, 0xffff0000, v204
	v_lshlrev_b32_e32 v90, 16, v205
	v_and_b32_e32 v91, 0xffff0000, v205
	v_lshlrev_b32_e32 v200, 16, v207
	v_and_b32_e32 v201, 0xffff0000, v207
	v_pk_fma_f32 v[86:87], v[86:87], v[134:135], v[90:91]
	v_pk_fma_f32 v[84:85], v[84:85], v[132:133], v[88:89]
	v_pk_fma_f32 v[88:89], v[82:83], v[130:131], v[200:201]
	v_pk_fma_f32 v[82:83], v[80:81], v[128:129], v[94:95]
	v_cvt_pk_bf16_f32 v80, v84, v85
	v_cvt_pk_bf16_f32 v81, v86, v87
	v_lshlrev_b32_e32 v84, 16, v210
	v_cvt_pk_bf16_f32 v82, v82, v83
	v_cvt_pk_bf16_f32 v83, v88, v89
	global_store_dwordx4 v[92:93], v[80:83], off offset:256
	v_and_b32_e32 v85, 0xffff0000, v210
	v_lshlrev_b32_e32 v86, 16, v211
	v_lshlrev_b32_e32 v80, 16, v208
	v_and_b32_e32 v81, 0xffff0000, v208
	v_and_b32_e32 v87, 0xffff0000, v211
	v_pk_fma_f32 v[76:77], v[76:77], v[140:141], v[80:81]
	v_lshlrev_b32_e32 v82, 16, v209
	v_and_b32_e32 v83, 0xffff0000, v209
	v_pk_fma_f32 v[80:81], v[74:75], v[138:139], v[86:87]
	v_pk_fma_f32 v[74:75], v[72:73], v[136:137], v[84:85]
	v_cvt_pk_bf16_f32 v72, v76, v77
	v_lshl_add_u64 v[76:77], s[6:7], 0, v[228:229]
	v_pk_fma_f32 v[78:79], v[78:79], v[142:143], v[82:83]
	v_lshl_add_u64 v[76:77], v[76:77], 0, v[154:155]
	v_cvt_pk_bf16_f32 v73, v78, v79
	v_cvt_pk_bf16_f32 v74, v74, v75
	v_cvt_pk_bf16_f32 v75, v80, v81
	global_store_dwordx4 v[76:77], v[72:75], off
	v_lshlrev_b32_e32 v78, 16, v224
	v_and_b32_e32 v79, 0xffff0000, v224
	v_lshlrev_b32_e32 v72, 16, v222
	v_and_b32_e32 v73, 0xffff0000, v222
	v_lshlrev_b32_e32 v80, 16, v225
	v_and_b32_e32 v81, 0xffff0000, v225
	v_lshlrev_b32_e32 v74, 16, v223
	v_and_b32_e32 v75, 0xffff0000, v223
	v_pk_fma_f32 v[68:69], v[68:69], v[132:133], v[72:73]
	v_pk_fma_f32 v[72:73], v[66:67], v[130:131], v[80:81]
	v_pk_fma_f32 v[66:67], v[64:65], v[128:129], v[78:79]
	v_pk_fma_f32 v[70:71], v[70:71], v[134:135], v[74:75]
	v_cvt_pk_bf16_f32 v64, v68, v69
	s_nop 0
	v_cvt_pk_bf16_f32 v65, v70, v71
	v_cvt_pk_bf16_f32 v66, v66, v67
	v_cvt_pk_bf16_f32 v67, v72, v73
	global_store_dwordx4 v[76:77], v[64:67], off offset:256
	s_mov_b64 s[14:15], 0xb0000
	v_lshl_add_u64 v[226:227], v[158:159], 0, s[58:59]
	v_lshl_add_u64 v[228:229], v[158:159], 0, s[14:15]
	v_lshl_add_u64 v[204:205], v[156:157], 0, v[226:227]
	v_lshl_add_u64 v[222:223], v[156:157], 0, v[228:229]
	global_load_dwordx4 v[200:203], v[204:205], off
	s_nop 0
	global_load_dwordx4 v[204:207], v[204:205], off offset:256
	s_nop 0
	global_load_dwordx4 v[208:211], v[222:223], off
	s_nop 0
	global_load_dwordx4 v[222:225], v[222:223], off offset:256
	s_waitcnt vmcnt(8)
; __device__ __forceinline__ float bf_lo(unsigned u) { return __uint_as_float(u << 16); }
; __device__ __forceinline__ float bf_hi(unsigned u) { return __uint_as_float(u & 0xffff0000u); }
; __device__ __forceinline__ u32x4 pack8(const f32x4 a, const f32x4 b) { u32x4 w; w.x = cvt_pk_bf16(a[0], a[1]); w.y = cvt_pk_bf16(a[2], a[3]); w.z = cvt_pk_bf16(b[0], b[1]); w.w = cvt_pk_bf16(b[2], b[3]); return w; }
; template <int NT, class Epi>
; __device__ __forceinline__ void gemm_phase(LAS unsigned char* lds, const int K, const Sched& S, const Epi& E, const int wave_s) {
;     ...
;         const bool keep = E(acc, cur, wr, wc, fr, fq);
;         __builtin_amdgcn_s_waitcnt(0x0F70);
;         if (!has_next) break;
;     __device__ __forceinline__ bool operator()(f32x4 (&acc)[2][2][4][2], const Unit& u, int wr, int wc, int fr, int fq) const {
;     ...
;         for (int b4 = 0; b4 < 4; ++b4) {
;             const int ai = b4 >> 1, mh = (b4 & 1) * 2;
;             u32x4 xq[2][2];
; #pragma unroll
;             for (int mm = 0; mm < 2; ++mm)
; #pragma unroll
;                 for (int bj = 0; bj < 2; ++bj) xq[mm][bj] = *(const u32x4*)(xb + (size_t)(row0 + ai * 128 + (mh + mm) * 16) * D + c0 + bj * 128);
;             __builtin_amdgcn_sched_barrier(0);
; #pragma unroll
;             for (int mm = 0; mm < 2; ++mm)
; #pragma unroll
;                 for (int bj = 0; bj < 2; ++bj)
;                 { const u32x4 q = xq[mm][bj]; const f32x4 x0 = (f32x4){bf_lo(q.x), bf_hi(q.x), bf_lo(q.y), bf_hi(q.y)}, x1 = (f32x4){bf_lo(q.z), bf_hi(q.z), bf_lo(q.w), bf_hi(q.w)};
;                     *(u32x4*)(xb + (size_t)(row0 + ai * 128 + (mh + mm) * 16) * D + c0 + bj * 128) = pack8(x0 + gv[bj][0] * acc[ai][bj][mh + mm][0], x1 + gv[bj][1] * acc[ai][bj][mh + mm][1]); }
;             __builtin_amdgcn_sched_barrier(0);
;         }
	v_lshlrev_b32_e32 v84, 16, v230
	v_and_b32_e32 v85, 0xffff0000, v230
	v_lshlrev_b32_e32 v230, 16, v231
	v_and_b32_e32 v231, 0xffff0000, v231
	v_lshlrev_b32_e32 v86, 16, v232
	v_and_b32_e32 v87, 0xffff0000, v232
	v_lshlrev_b32_e32 v232, 16, v233
	v_and_b32_e32 v233, 0xffff0000, v233
	v_pk_fma_f32 v[60:61], v[60:61], v[140:141], v[84:85]
	v_pk_fma_f32 v[62:63], v[62:63], v[142:143], v[230:231]
	v_pk_fma_f32 v[230:231], v[58:59], v[138:139], v[232:233]
	v_pk_fma_f32 v[58:59], v[56:57], v[136:137], v[86:87]
	v_cvt_pk_bf16_f32 v56, v60, v61
	v_lshl_add_u64 v[60:61], s[6:7], 0, v[242:243]
	v_cvt_pk_bf16_f32 v57, v62, v63
	v_cvt_pk_bf16_f32 v58, v58, v59
	v_cvt_pk_bf16_f32 v59, v230, v231
	v_lshl_add_u64 v[60:61], v[60:61], 0, v[154:155]
	global_store_dwordx4 v[60:61], v[56:59], off
	v_lshlrev_b32_e32 v62, 16, v236
	v_and_b32_e32 v63, 0xffff0000, v236
	v_lshlrev_b32_e32 v56, 16, v234
	v_and_b32_e32 v57, 0xffff0000, v234
	v_lshlrev_b32_e32 v58, 16, v235
	v_and_b32_e32 v59, 0xffff0000, v235
	v_lshlrev_b32_e32 v230, 16, v237
	v_and_b32_e32 v231, 0xffff0000, v237
	v_pk_fma_f32 v[54:55], v[54:55], v[134:135], v[58:59]
	v_pk_fma_f32 v[52:53], v[52:53], v[132:133], v[56:57]
	v_pk_fma_f32 v[56:57], v[50:51], v[130:131], v[230:231]
	v_pk_fma_f32 v[50:51], v[48:49], v[128:129], v[62:63]
	v_cvt_pk_bf16_f32 v48, v52, v53
	v_cvt_pk_bf16_f32 v49, v54, v55
	v_lshlrev_b32_e32 v52, 16, v240
	v_cvt_pk_bf16_f32 v50, v50, v51
	v_cvt_pk_bf16_f32 v51, v56, v57
	global_store_dwordx4 v[60:61], v[48:51], off offset:256
	v_and_b32_e32 v53, 0xffff0000, v240
	v_lshlrev_b32_e32 v54, 16, v241
	v_lshlrev_b32_e32 v48, 16, v238
	v_and_b32_e32 v49, 0xffff0000, v238
	v_and_b32_e32 v55, 0xffff0000, v241
	v_pk_fma_f32 v[44:45], v[44:45], v[140:141], v[48:49]
	v_lshlrev_b32_e32 v50, 16, v239
	v_and_b32_e32 v51, 0xffff0000, v239
	v_pk_fma_f32 v[48:49], v[42:43], v[138:139], v[54:55]
	v_pk_fma_f32 v[42:43], v[40:41], v[136:137], v[52:53]
	v_cvt_pk_bf16_f32 v40, v44, v45
	v_lshl_add_u64 v[44:45], s[6:7], 0, v[250:251]
	v_pk_fma_f32 v[46:47], v[46:47], v[142:143], v[50:51]
	v_lshl_add_u64 v[44:45], v[44:45], 0, v[154:155]
	v_cvt_pk_bf16_f32 v41, v46, v47
	v_cvt_pk_bf16_f32 v42, v42, v43
	v_cvt_pk_bf16_f32 v43, v48, v49
	global_store_dwordx4 v[44:45], v[40:43], off
	v_lshlrev_b32_e32 v46, 16, v248
	v_and_b32_e32 v47, 0xffff0000, v248
	v_lshlrev_b32_e32 v40, 16, v246
	v_and_b32_e32 v41, 0xffff0000, v246
	v_lshlrev_b32_e32 v48, 16, v249
	v_and_b32_e32 v49, 0xffff0000, v249
	v_lshlrev_b32_e32 v42, 16, v247
	v_and_b32_e32 v43, 0xffff0000, v247
	v_pk_fma_f32 v[36:37], v[36:37], v[132:133], v[40:41]
	v_pk_fma_f32 v[40:41], v[34:35], v[130:131], v[48:49]
	v_pk_fma_f32 v[34:35], v[32:33], v[128:129], v[46:47]
	v_pk_fma_f32 v[38:39], v[38:39], v[134:135], v[42:43]
	v_cvt_pk_bf16_f32 v32, v36, v37
	s_nop 0
	v_cvt_pk_bf16_f32 v33, v38, v39
	v_cvt_pk_bf16_f32 v34, v34, v35
	v_cvt_pk_bf16_f32 v35, v40, v41
	global_store_dwordx4 v[44:45], v[32:35], off offset:256
	s_waitcnt vmcnt(4)
	v_lshlrev_b32_e32 v52, 16, v200
	v_and_b32_e32 v53, 0xffff0000, v200
	v_lshlrev_b32_e32 v200, 16, v201
	v_and_b32_e32 v201, 0xffff0000, v201
	v_lshlrev_b32_e32 v54, 16, v202
	v_and_b32_e32 v55, 0xffff0000, v202
	v_lshlrev_b32_e32 v202, 16, v203
	v_and_b32_e32 v203, 0xffff0000, v203
	v_pk_fma_f32 v[28:29], v[28:29], v[140:141], v[52:53]
	v_pk_fma_f32 v[30:31], v[30:31], v[142:143], v[200:201]
	v_pk_fma_f32 v[200:201], v[26:27], v[138:139], v[202:203]
	v_pk_fma_f32 v[26:27], v[24:25], v[136:137], v[54:55]
	v_cvt_pk_bf16_f32 v24, v28, v29
	v_lshl_add_u64 v[28:29], s[6:7], 0, v[226:227]
	v_cvt_pk_bf16_f32 v25, v30, v31
	v_cvt_pk_bf16_f32 v26, v26, v27
	v_cvt_pk_bf16_f32 v27, v200, v201
	v_lshl_add_u64 v[28:29], v[28:29], 0, v[154:155]
	global_store_dwordx4 v[28:29], v[24:27], off
	v_lshlrev_b32_e32 v30, 16, v206
	v_and_b32_e32 v31, 0xffff0000, v206
	v_lshlrev_b32_e32 v24, 16, v204
	v_and_b32_e32 v25, 0xffff0000, v204
	v_lshlrev_b32_e32 v26, 16, v205
	v_and_b32_e32 v27, 0xffff0000, v205
	v_lshlrev_b32_e32 v200, 16, v207
	v_and_b32_e32 v201, 0xffff0000, v207
	v_pk_fma_f32 v[22:23], v[22:23], v[134:135], v[26:27]
	v_pk_fma_f32 v[20:21], v[20:21], v[132:133], v[24:25]
	v_pk_fma_f32 v[24:25], v[18:19], v[130:131], v[200:201]
	v_pk_fma_f32 v[18:19], v[16:17], v[128:129], v[30:31]
	v_cvt_pk_bf16_f32 v16, v20, v21
	v_cvt_pk_bf16_f32 v17, v22, v23
	v_lshlrev_b32_e32 v20, 16, v210
	v_cvt_pk_bf16_f32 v18, v18, v19
	v_cvt_pk_bf16_f32 v19, v24, v25
	global_store_dwordx4 v[28:29], v[16:19], off offset:256
	v_and_b32_e32 v21, 0xffff0000, v210
	v_lshlrev_b32_e32 v22, 16, v211
	v_lshlrev_b32_e32 v16, 16, v208
	v_and_b32_e32 v17, 0xffff0000, v208
	v_and_b32_e32 v23, 0xffff0000, v211
	v_pk_fma_f32 v[12:13], v[12:13], v[140:141], v[16:17]
	v_lshlrev_b32_e32 v18, 16, v209
	v_and_b32_e32 v19, 0xffff0000, v209
	v_pk_fma_f32 v[16:17], v[10:11], v[138:139], v[22:23]
	v_pk_fma_f32 v[10:11], v[8:9], v[136:137], v[20:21]
	v_cvt_pk_bf16_f32 v8, v12, v13
	v_lshl_add_u64 v[12:13], s[6:7], 0, v[228:229]
	v_pk_fma_f32 v[14:15], v[14:15], v[142:143], v[18:19]
	v_lshl_add_u64 v[12:13], v[12:13], 0, v[154:155]
	v_cvt_pk_bf16_f32 v9, v14, v15
	v_cvt_pk_bf16_f32 v10, v10, v11
	v_cvt_pk_bf16_f32 v11, v16, v17
	global_store_dwordx4 v[12:13], v[8:11], off
	v_lshlrev_b32_e32 v14, 16, v224
	v_and_b32_e32 v15, 0xffff0000, v224
	v_lshlrev_b32_e32 v8, 16, v222
	v_and_b32_e32 v9, 0xffff0000, v222
	v_lshlrev_b32_e32 v16, 16, v225
	v_and_b32_e32 v17, 0xffff0000, v225
	v_lshlrev_b32_e32 v10, 16, v223
	v_and_b32_e32 v11, 0xffff0000, v223
	v_pk_fma_f32 v[4:5], v[4:5], v[132:133], v[8:9]
	v_pk_fma_f32 v[8:9], v[2:3], v[130:131], v[16:17]
	v_pk_fma_f32 v[2:3], v[0:1], v[128:129], v[14:15]
	v_pk_fma_f32 v[6:7], v[6:7], v[134:135], v[10:11]
	v_cvt_pk_bf16_f32 v0, v4, v5
	s_nop 0
	v_cvt_pk_bf16_f32 v1, v6, v7
	v_cvt_pk_bf16_f32 v2, v2, v3
	v_cvt_pk_bf16_f32 v3, v8, v9
	global_store_dwordx4 v[12:13], v[0:3], off offset:256
	v_readlane_b32 s40, v255, 38
	s_andn2_b64 vcc, exec, s[38:39]
	s_mov_b64 s[28:29], -1
	v_readlane_b32 s97, v255, 18
	v_readlane_b32 s41, v255, 39
	s_waitcnt vmcnt(0)
	s_cbranch_vccnz .LBB0_109
	s_andn2_b64 vcc, exec, s[8:9]
	s_cbranch_vccnz .LBB0_108
	s_barrier
	s_branch .LBB0_108

; __global__ void __launch_bounds__(512, 2) fwd_kernel(const Args a) {
;     ...
;             for (int it = bx; it < DEPTH * 192; it += G) {
;                 const int l = it / 192, j0 = (it % 192) * 64;
;                 const float* wp = ada_w + (size_t)l * D * 12288 + (size_t)(wave * 256) * 12288 + j0 + lane;
;                 float a0 = 0.f, a1 = 0.f, a2 = 0.f;
; #pragma unroll 8
;                 for (int k = 0; k < 256; ++k) { const float w = wp[(size_t)k * 12288]; const int kk = wave * 256 + k; a0 += sl[kk] * w; a1 += sl[2048 + kk] * w; a2 += sl[4096 + kk] * w; }
;                 red[(wave * 3 + 0) * 64 + lane] = a0; red[(wave * 3 + 1) * 64 + lane] = a1; red[(wave * 3 + 2) * 64 + lane] = a2;
.LBB0_533:
	s_mul_hi_i32 s0, s2, 0x2aaaaaab
	s_lshr_b32 s1, s0, 31
	s_ashr_i32 s4, s0, 5
	s_add_i32 s4, s4, s1
	s_mul_i32 s0, s4, 0xc0
	s_sub_i32 s0, s2, s0
	s_lshl_b32 s8, s0, 6
	s_mul_i32 s1, s4, 0x6000000
	s_mul_hi_i32 s0, s4, 0x6000000
	s_add_u32 s10, s45, s1
	s_addc_u32 s11, s53, s0
	s_ashr_i32 s9, s8, 31
	s_lshl_b64 s[0:1], s[8:9], 2
	s_add_u32 s0, s10, s0
	s_addc_u32 s1, s11, s1
	v_mov_b32_e32 v7, 0
	v_lshl_add_u64 v[2:3], s[0:1], 0, v[176:177]
	s_mov_b64 s[10:11], 0
	s_mov_b32 s9, s60
	v_mov_b32_e32 v4, 0
	v_mov_b32_e32 v5, v7
	v_mov_b32_e32 v28, s60
	s_mov_b32 s10, 7
	global_load_dword v32, v176, s[0:1]
	s_add_u32 s0, s0, 0xc000
	s_addc_u32 s1, s1, 0
	global_load_dword v33, v176, s[0:1]
	s_add_u32 s0, s0, 0xc000
	s_addc_u32 s1, s1, 0
	global_load_dword v34, v176, s[0:1]
	s_add_u32 s0, s0, 0xc000
	s_addc_u32 s1, s1, 0
	global_load_dword v35, v176, s[0:1]
	s_add_u32 s0, s0, 0xc000
	s_addc_u32 s1, s1, 0
	global_load_dword v36, v176, s[0:1]
	s_add_u32 s0, s0, 0xc000
	s_addc_u32 s1, s1, 0
	global_load_dword v37, v176, s[0:1]
	s_add_u32 s0, s0, 0xc000
	s_addc_u32 s1, s1, 0
	global_load_dword v38, v176, s[0:1]
	s_add_u32 s0, s0, 0xc000
	s_addc_u32 s1, s1, 0
	global_load_dword v39, v176, s[0:1]
	s_add_u32 s0, s0, 0xc000
	s_addc_u32 s1, s1, 0
	global_load_dword v40, v176, s[0:1]
	s_add_u32 s0, s0, 0xc000
	s_addc_u32 s1, s1, 0
	global_load_dword v41, v176, s[0:1]
	s_add_u32 s0, s0, 0xc000
	s_addc_u32 s1, s1, 0
	global_load_dword v42, v176, s[0:1]
	s_add_u32 s0, s0, 0xc000
	s_addc_u32 s1, s1, 0
	global_load_dword v43, v176, s[0:1]
	s_add_u32 s0, s0, 0xc000
	s_addc_u32 s1, s1, 0
	global_load_dword v44, v176, s[0:1]
	s_add_u32 s0, s0, 0xc000
	s_addc_u32 s1, s1, 0
	global_load_dword v45, v176, s[0:1]
	s_add_u32 s0, s0, 0xc000
	s_addc_u32 s1, s1, 0
	global_load_dword v46, v176, s[0:1]
	s_add_u32 s0, s0, 0xc000
	s_addc_u32 s1, s1, 0
	global_load_dword v47, v176, s[0:1]
	s_add_u32 s0, s0, 0xc000
	s_addc_u32 s1, s1, 0
.Lada_loop:
	global_load_dword v64, v176, s[0:1]
	s_add_u32 s0, s0, 0xc000
	s_addc_u32 s1, s1, 0
	global_load_dword v65, v176, s[0:1]
	s_add_u32 s0, s0, 0xc000
	s_addc_u32 s1, s1, 0
	global_load_dword v66, v176, s[0:1]
	s_add_u32 s0, s0, 0xc000
	s_addc_u32 s1, s1, 0
	global_load_dword v67, v176, s[0:1]
	s_add_u32 s0, s0, 0xc000
	s_addc_u32 s1, s1, 0
	global_load_dword v68, v176, s[0:1]
	s_add_u32 s0, s0, 0xc000
	s_addc_u32 s1, s1, 0
	global_load_dword v69, v176, s[0:1]
	s_add_u32 s0, s0, 0xc000
	s_addc_u32 s1, s1, 0
	global_load_dword v70, v176, s[0:1]
	s_add_u32 s0, s0, 0xc000
	s_addc_u32 s1, s1, 0
	global_load_dword v71, v176, s[0:1]
	s_add_u32 s0, s0, 0xc000
	s_addc_u32 s1, s1, 0
	global_load_dword v72, v176, s[0:1]
	s_add_u32 s0, s0, 0xc000
	s_addc_u32 s1, s1, 0
	global_load_dword v73, v176, s[0:1]
	s_add_u32 s0, s0, 0xc000
	s_addc_u32 s1, s1, 0
	global_load_dword v74, v176, s[0:1]
	s_add_u32 s0, s0, 0xc000
	s_addc_u32 s1, s1, 0
	global_load_dword v75, v176, s[0:1]
	s_add_u32 s0, s0, 0xc000
	s_addc_u32 s1, s1, 0
	global_load_dword v76, v176, s[0:1]
	s_add_u32 s0, s0, 0xc000
	s_addc_u32 s1, s1, 0
	global_load_dword v77, v176, s[0:1]
	s_add_u32 s0, s0, 0xc000
	s_addc_u32 s1, s1, 0
	global_load_dword v78, v176, s[0:1]
	s_add_u32 s0, s0, 0xc000
	s_addc_u32 s1, s1, 0
	global_load_dword v79, v176, s[0:1]
	s_add_u32 s0, s0, 0xc000
	s_addc_u32 s1, s1, 0
	ds_read_b128 v[96:99], v28
	ds_read_b128 v[100:103], v28 offset:16
	ds_read_b128 v[104:107], v28 offset:32
	ds_read_b128 v[108:111], v28 offset:48
	ds_read_b128 v[112:115], v28 offset:8192
	ds_read_b128 v[116:119], v28 offset:8208
	ds_read_b128 v[120:123], v28 offset:8224
	ds_read_b128 v[124:127], v28 offset:8240
	ds_read_b128 v[128:131], v28 offset:16384
	ds_read_b128 v[132:135], v28 offset:16400
	ds_read_b128 v[136:139], v28 offset:16416
	ds_read_b128 v[140:143], v28 offset:16432
	s_waitcnt vmcnt(16)
	s_waitcnt lgkmcnt(0)
	v_fmac_f32_e32 v4, v32, v96
	v_fmac_f32_e32 v5, v32, v112
	v_fmac_f32_e32 v7, v32, v128
	v_fmac_f32_e32 v4, v33, v97
	v_fmac_f32_e32 v5, v33, v113
	v_fmac_f32_e32 v7, v33, v129
	v_fmac_f32_e32 v4, v34, v98
	v_fmac_f32_e32 v5, v34, v114
	v_fmac_f32_e32 v7, v34, v130
	v_fmac_f32_e32 v4, v35, v99
	v_fmac_f32_e32 v5, v35, v115
	v_fmac_f32_e32 v7, v35, v131
	v_fmac_f32_e32 v4, v36, v100
	v_fmac_f32_e32 v5, v36, v116
	v_fmac_f32_e32 v7, v36, v132
	v_fmac_f32_e32 v4, v37, v101
	v_fmac_f32_e32 v5, v37, v117
	v_fmac_f32_e32 v7, v37, v133
	v_fmac_f32_e32 v4, v38, v102
	v_fmac_f32_e32 v5, v38, v118
	v_fmac_f32_e32 v7, v38, v134
	v_fmac_f32_e32 v4, v39, v103
	v_fmac_f32_e32 v5, v39, v119
	v_fmac_f32_e32 v7, v39, v135
	v_fmac_f32_e32 v4, v40, v104
	v_fmac_f32_e32 v5, v40, v120
	v_fmac_f32_e32 v7, v40, v136
	v_fmac_f32_e32 v4, v41, v105
	v_fmac_f32_e32 v5, v41, v121
	v_fmac_f32_e32 v7, v41, v137
	v_fmac_f32_e32 v4, v42, v106
	v_fmac_f32_e32 v5, v42, v122
	v_fmac_f32_e32 v7, v42, v138
	v_fmac_f32_e32 v4, v43, v107
	v_fmac_f32_e32 v5, v43, v123
	v_fmac_f32_e32 v7, v43, v139
	v_fmac_f32_e32 v4, v44, v108
	v_fmac_f32_e32 v5, v44, v124
	v_fmac_f32_e32 v7, v44, v140
	v_fmac_f32_e32 v4, v45, v109
	v_fmac_f32_e32 v5, v45, v125
	v_fmac_f32_e32 v7, v45, v141
	v_fmac_f32_e32 v4, v46, v110
	v_fmac_f32_e32 v5, v46, v126
	v_fmac_f32_e32 v7, v46, v142
	v_fmac_f32_e32 v4, v47, v111
	v_fmac_f32_e32 v5, v47, v127
	v_fmac_f32_e32 v7, v47, v143
	v_add_u32_e32 v28, 64, v28
	global_load_dword v32, v176, s[0:1]
	s_add_u32 s0, s0, 0xc000
	s_addc_u32 s1, s1, 0
	global_load_dword v33, v176, s[0:1]
	s_add_u32 s0, s0, 0xc000
	s_addc_u32 s1, s1, 0
	global_load_dword v34, v176, s[0:1]
	s_add_u32 s0, s0, 0xc000
	s_addc_u32 s1, s1, 0
	global_load_dword v35, v176, s[0:1]
	s_add_u32 s0, s0, 0xc000
	s_addc_u32 s1, s1, 0
; __global__ void __launch_bounds__(512, 2) fwd_kernel(const Args a) {
;     ...
; #pragma unroll 8
;                 for (int k = 0; k < 256; ++k) { const float w = wp[(size_t)k * 12288]; const int kk = wave * 256 + k; a0 += sl[kk] * w; a1 += sl[2048 + kk] * w; a2 += sl[4096 + kk] * w; }
	global_load_dword v36, v176, s[0:1]
	s_add_u32 s0, s0, 0xc000
	s_addc_u32 s1, s1, 0
	global_load_dword v37, v176, s[0:1]
	s_add_u32 s0, s0, 0xc000
	s_addc_u32 s1, s1, 0
	global_load_dword v38, v176, s[0:1]
	s_add_u32 s0, s0, 0xc000
	s_addc_u32 s1, s1, 0
	global_load_dword v39, v176, s[0:1]
	s_add_u32 s0, s0, 0xc000
	s_addc_u32 s1, s1, 0
	global_load_dword v40, v176, s[0:1]
	s_add_u32 s0, s0, 0xc000
	s_addc_u32 s1, s1, 0
	global_load_dword v41, v176, s[0:1]
	s_add_u32 s0, s0, 0xc000
	s_addc_u32 s1, s1, 0
	global_load_dword v42, v176, s[0:1]
	s_add_u32 s0, s0, 0xc000
	s_addc_u32 s1, s1, 0
	global_load_dword v43, v176, s[0:1]
	s_add_u32 s0, s0, 0xc000
	s_addc_u32 s1, s1, 0
	global_load_dword v44, v176, s[0:1]
	s_add_u32 s0, s0, 0xc000
	s_addc_u32 s1, s1, 0
	global_load_dword v45, v176, s[0:1]
	s_add_u32 s0, s0, 0xc000
	s_addc_u32 s1, s1, 0
	global_load_dword v46, v176, s[0:1]
	s_add_u32 s0, s0, 0xc000
	s_addc_u32 s1, s1, 0
	global_load_dword v47, v176, s[0:1]
	s_add_u32 s0, s0, 0xc000
	s_addc_u32 s1, s1, 0
	ds_read_b128 v[96:99], v28
	ds_read_b128 v[100:103], v28 offset:16
	ds_read_b128 v[104:107], v28 offset:32
	ds_read_b128 v[108:111], v28 offset:48
	ds_read_b128 v[112:115], v28 offset:8192
	ds_read_b128 v[116:119], v28 offset:8208
	ds_read_b128 v[120:123], v28 offset:8224
	ds_read_b128 v[124:127], v28 offset:8240
	ds_read_b128 v[128:131], v28 offset:16384
	ds_read_b128 v[132:135], v28 offset:16400
	ds_read_b128 v[136:139], v28 offset:16416
	ds_read_b128 v[140:143], v28 offset:16432
	s_waitcnt vmcnt(16)
	s_waitcnt lgkmcnt(0)
	v_fmac_f32_e32 v4, v64, v96
	v_fmac_f32_e32 v5, v64, v112
	v_fmac_f32_e32 v7, v64, v128
	v_fmac_f32_e32 v4, v65, v97
	v_fmac_f32_e32 v5, v65, v113
	v_fmac_f32_e32 v7, v65, v129
	v_fmac_f32_e32 v4, v66, v98
	v_fmac_f32_e32 v5, v66, v114
	v_fmac_f32_e32 v7, v66, v130
	v_fmac_f32_e32 v4, v67, v99
	v_fmac_f32_e32 v5, v67, v115
	v_fmac_f32_e32 v7, v67, v131
	v_fmac_f32_e32 v4, v68, v100
	v_fmac_f32_e32 v5, v68, v116
	v_fmac_f32_e32 v7, v68, v132
	v_fmac_f32_e32 v4, v69, v101
	v_fmac_f32_e32 v5, v69, v117
	v_fmac_f32_e32 v7, v69, v133
	v_fmac_f32_e32 v4, v70, v102
	v_fmac_f32_e32 v5, v70, v118
	v_fmac_f32_e32 v7, v70, v134
	v_fmac_f32_e32 v4, v71, v103
	v_fmac_f32_e32 v5, v71, v119
	v_fmac_f32_e32 v7, v71, v135
	v_fmac_f32_e32 v4, v72, v104
	v_fmac_f32_e32 v5, v72, v120
	v_fmac_f32_e32 v7, v72, v136
	v_fmac_f32_e32 v4, v73, v105
	v_fmac_f32_e32 v5, v73, v121
	v_fmac_f32_e32 v7, v73, v137
	v_fmac_f32_e32 v4, v74, v106
	v_fmac_f32_e32 v5, v74, v122
	v_fmac_f32_e32 v7, v74, v138
	v_fmac_f32_e32 v4, v75, v107
	v_fmac_f32_e32 v5, v75, v123
	v_fmac_f32_e32 v7, v75, v139
	v_fmac_f32_e32 v4, v76, v108
	v_fmac_f32_e32 v5, v76, v124
	v_fmac_f32_e32 v7, v76, v140
	v_fmac_f32_e32 v4, v77, v109
	v_fmac_f32_e32 v5, v77, v125
	v_fmac_f32_e32 v7, v77, v141
	v_fmac_f32_e32 v4, v78, v110
	v_fmac_f32_e32 v5, v78, v126
	v_fmac_f32_e32 v7, v78, v142
	v_fmac_f32_e32 v4, v79, v111
	v_fmac_f32_e32 v5, v79, v127
	v_fmac_f32_e32 v7, v79, v143
	v_add_u32_e32 v28, 64, v28
	s_add_i32 s10, s10, -1
	s_cmp_lg_u32 s10, 0
	s_cbranch_scc1 .Lada_loop
	global_load_dword v64, v176, s[0:1]
	s_add_u32 s0, s0, 0xc000
	s_addc_u32 s1, s1, 0
	global_load_dword v65, v176, s[0:1]
	s_add_u32 s0, s0, 0xc000
	s_addc_u32 s1, s1, 0
	global_load_dword v66, v176, s[0:1]
	s_add_u32 s0, s0, 0xc000
	s_addc_u32 s1, s1, 0
	global_load_dword v67, v176, s[0:1]
	s_add_u32 s0, s0, 0xc000
	s_addc_u32 s1, s1, 0
	global_load_dword v68, v176, s[0:1]
	s_add_u32 s0, s0, 0xc000
	s_addc_u32 s1, s1, 0
	global_load_dword v69, v176, s[0:1]
	s_add_u32 s0, s0, 0xc000
	s_addc_u32 s1, s1, 0
	global_load_dword v70, v176, s[0:1]
	s_add_u32 s0, s0, 0xc000
	s_addc_u32 s1, s1, 0
	global_load_dword v71, v176, s[0:1]
	s_add_u32 s0, s0, 0xc000
	s_addc_u32 s1, s1, 0
	global_load_dword v72, v176, s[0:1]
	s_add_u32 s0, s0, 0xc000
	s_addc_u32 s1, s1, 0
	global_load_dword v73, v176, s[0:1]
	s_add_u32 s0, s0, 0xc000
	s_addc_u32 s1, s1, 0
	global_load_dword v74, v176, s[0:1]
	s_add_u32 s0, s0, 0xc000
	s_addc_u32 s1, s1, 0
	global_load_dword v75, v176, s[0:1]
	s_add_u32 s0, s0, 0xc000
	s_addc_u32 s1, s1, 0
	global_load_dword v76, v176, s[0:1]
	s_add_u32 s0, s0, 0xc000
	s_addc_u32 s1, s1, 0
	global_load_dword v77, v176, s[0:1]
	s_add_u32 s0, s0, 0xc000
	s_addc_u32 s1, s1, 0
	global_load_dword v78, v176, s[0:1]
	s_add_u32 s0, s0, 0xc000
	s_addc_u32 s1, s1, 0
	global_load_dword v79, v176, s[0:1]
	s_add_u32 s0, s0, 0xc000
	s_addc_u32 s1, s1, 0
	ds_read_b128 v[96:99], v28
	ds_read_b128 v[100:103], v28 offset:16
	ds_read_b128 v[104:107], v28 offset:32
	ds_read_b128 v[108:111], v28 offset:48
	ds_read_b128 v[112:115], v28 offset:8192
	ds_read_b128 v[116:119], v28 offset:8208
	ds_read_b128 v[120:123], v28 offset:8224
	ds_read_b128 v[124:127], v28 offset:8240
	ds_read_b128 v[128:131], v28 offset:16384
	ds_read_b128 v[132:135], v28 offset:16400
	ds_read_b128 v[136:139], v28 offset:16416
	ds_read_b128 v[140:143], v28 offset:16432
	s_waitcnt vmcnt(16)
	s_waitcnt lgkmcnt(0)
; __global__ void __launch_bounds__(512, 2) fwd_kernel(const Args a) {
;     ...
; #pragma unroll 8
;                 for (int k = 0; k < 256; ++k) { const float w = wp[(size_t)k * 12288]; const int kk = wave * 256 + k; a0 += sl[kk] * w; a1 += sl[2048 + kk] * w; a2 += sl[4096 + kk] * w; }
;                 red[(wave * 3 + 0) * 64 + lane] = a0; red[(wave * 3 + 1) * 64 + lane] = a1; red[(wave * 3 + 2) * 64 + lane] = a2;
;                 __syncthreads();
;                 if (tid < 192) { const int v = tid >> 6, jl = tid & 63; float s = ada_b[l * 12288 + j0 + jl];
; #pragma unroll
;                     for (int w8 = 0; w8 < 8; ++w8) s += red[(w8 * 3 + v) * 64 + jl];
;                     ADA[(l * 3 + v) * 12288 + j0 + jl] = s; }
;                 __syncthreads();
	v_fmac_f32_e32 v4, v32, v96
	v_fmac_f32_e32 v5, v32, v112
	v_fmac_f32_e32 v7, v32, v128
	v_fmac_f32_e32 v4, v33, v97
	v_fmac_f32_e32 v5, v33, v113
	v_fmac_f32_e32 v7, v33, v129
	v_fmac_f32_e32 v4, v34, v98
	v_fmac_f32_e32 v5, v34, v114
	v_fmac_f32_e32 v7, v34, v130
	v_fmac_f32_e32 v4, v35, v99
	v_fmac_f32_e32 v5, v35, v115
	v_fmac_f32_e32 v7, v35, v131
	v_fmac_f32_e32 v4, v36, v100
	v_fmac_f32_e32 v5, v36, v116
	v_fmac_f32_e32 v7, v36, v132
	v_fmac_f32_e32 v4, v37, v101
	v_fmac_f32_e32 v5, v37, v117
	v_fmac_f32_e32 v7, v37, v133
	v_fmac_f32_e32 v4, v38, v102
	v_fmac_f32_e32 v5, v38, v118
	v_fmac_f32_e32 v7, v38, v134
	v_fmac_f32_e32 v4, v39, v103
	v_fmac_f32_e32 v5, v39, v119
	v_fmac_f32_e32 v7, v39, v135
	v_fmac_f32_e32 v4, v40, v104
	v_fmac_f32_e32 v5, v40, v120
	v_fmac_f32_e32 v7, v40, v136
	v_fmac_f32_e32 v4, v41, v105
	v_fmac_f32_e32 v5, v41, v121
	v_fmac_f32_e32 v7, v41, v137
	v_fmac_f32_e32 v4, v42, v106
	v_fmac_f32_e32 v5, v42, v122
	v_fmac_f32_e32 v7, v42, v138
	v_fmac_f32_e32 v4, v43, v107
	v_fmac_f32_e32 v5, v43, v123
	v_fmac_f32_e32 v7, v43, v139
	v_fmac_f32_e32 v4, v44, v108
	v_fmac_f32_e32 v5, v44, v124
	v_fmac_f32_e32 v7, v44, v140
	v_fmac_f32_e32 v4, v45, v109
	v_fmac_f32_e32 v5, v45, v125
	v_fmac_f32_e32 v7, v45, v141
	v_fmac_f32_e32 v4, v46, v110
	v_fmac_f32_e32 v5, v46, v126
	v_fmac_f32_e32 v7, v46, v142
	v_fmac_f32_e32 v4, v47, v111
	v_fmac_f32_e32 v5, v47, v127
	v_fmac_f32_e32 v7, v47, v143
	v_add_u32_e32 v28, 64, v28
	ds_read_b128 v[96:99], v28
	ds_read_b128 v[100:103], v28 offset:16
	ds_read_b128 v[104:107], v28 offset:32
	ds_read_b128 v[108:111], v28 offset:48
	ds_read_b128 v[112:115], v28 offset:8192
	ds_read_b128 v[116:119], v28 offset:8208
	ds_read_b128 v[120:123], v28 offset:8224
	ds_read_b128 v[124:127], v28 offset:8240
	ds_read_b128 v[128:131], v28 offset:16384
	ds_read_b128 v[132:135], v28 offset:16400
	ds_read_b128 v[136:139], v28 offset:16416
	ds_read_b128 v[140:143], v28 offset:16432
	s_waitcnt vmcnt(0)
	s_waitcnt lgkmcnt(0)
	v_fmac_f32_e32 v4, v64, v96
	v_fmac_f32_e32 v5, v64, v112
	v_fmac_f32_e32 v7, v64, v128
	v_fmac_f32_e32 v4, v65, v97
	v_fmac_f32_e32 v5, v65, v113
	v_fmac_f32_e32 v7, v65, v129
	v_fmac_f32_e32 v4, v66, v98
	v_fmac_f32_e32 v5, v66, v114
	v_fmac_f32_e32 v7, v66, v130
	v_fmac_f32_e32 v4, v67, v99
	v_fmac_f32_e32 v5, v67, v115
	v_fmac_f32_e32 v7, v67, v131
	v_fmac_f32_e32 v4, v68, v100
	v_fmac_f32_e32 v5, v68, v116
	v_fmac_f32_e32 v7, v68, v132
	v_fmac_f32_e32 v4, v69, v101
	v_fmac_f32_e32 v5, v69, v117
	v_fmac_f32_e32 v7, v69, v133
	v_fmac_f32_e32 v4, v70, v102
	v_fmac_f32_e32 v5, v70, v118
	v_fmac_f32_e32 v7, v70, v134
	v_fmac_f32_e32 v4, v71, v103
	v_fmac_f32_e32 v5, v71, v119
	v_fmac_f32_e32 v7, v71, v135
	v_fmac_f32_e32 v4, v72, v104
	v_fmac_f32_e32 v5, v72, v120
	v_fmac_f32_e32 v7, v72, v136
	v_fmac_f32_e32 v4, v73, v105
	v_fmac_f32_e32 v5, v73, v121
	v_fmac_f32_e32 v7, v73, v137
	v_fmac_f32_e32 v4, v74, v106
	v_fmac_f32_e32 v5, v74, v122
	v_fmac_f32_e32 v7, v74, v138
	v_fmac_f32_e32 v4, v75, v107
	v_fmac_f32_e32 v5, v75, v123
	v_fmac_f32_e32 v7, v75, v139
	v_fmac_f32_e32 v4, v76, v108
	v_fmac_f32_e32 v5, v76, v124
	v_fmac_f32_e32 v7, v76, v140
	v_fmac_f32_e32 v4, v77, v109
	v_fmac_f32_e32 v5, v77, v125
	v_fmac_f32_e32 v7, v77, v141
	v_fmac_f32_e32 v4, v78, v110
	v_fmac_f32_e32 v5, v78, v126
	v_fmac_f32_e32 v7, v78, v142
	v_fmac_f32_e32 v4, v79, v111
	v_fmac_f32_e32 v5, v79, v127
	v_fmac_f32_e32 v7, v79, v143
	v_add_u32_e32 v28, 64, v28
	ds_write2st64_b32 v1, v4, v5 offset0:96 offset1:97
	ds_write_b32 v1, v7 offset:25088
	s_waitcnt lgkmcnt(0)
	s_barrier
	s_and_saveexec_b64 s[0:1], vcc
	s_cbranch_execz .LBB0_532
	s_mul_i32 s9, s4, 0x3000
	s_add_i32 s9, s9, s8
	v_or_b32_e32 v2, s9, v188
	v_readlane_b32 s12, v252, 18
	v_ashrrev_i32_e32 v3, 31, v2
	v_readlane_b32 s22, v252, 28
	v_readlane_b32 s23, v252, 29
	v_mad_u64_u32 v[12:13], s[10:11], s4, 3, v[0:1]
	s_nop 0
	v_lshl_add_u64 v[2:3], v[2:3], 2, s[22:23]
	global_load_dword v7, v[2:3], off
	ds_read2st64_b32 v[2:3], v6 offset0:96 offset1:99
	ds_read2st64_b32 v[4:5], v6 offset0:102 offset1:105
	ds_read2st64_b32 v[8:9], v6 offset0:108 offset1:111
	ds_read2st64_b32 v[10:11], v6 offset0:114 offset1:117
	s_movk_i32 s4, 0x3000
	v_mul_lo_u32 v12, v12, s4
	v_add_u32_e32 v12, s8, v12
	v_readlane_b32 s16, v252, 22
	v_readlane_b32 s17, v252, 23
	v_or_b32_e32 v12, v12, v188
	v_readlane_b32 s16, v255, 42
	v_readlane_b32 s22, v255, 40
	v_ashrrev_i32_e32 v13, 31, v12
	v_readlane_b32 s17, v255, 43
	v_readlane_b32 s23, v255, 41
	v_readlane_b32 s13, v252, 19
	v_readlane_b32 s14, v252, 20
	v_readlane_b32 s15, v252, 21
	v_readlane_b32 s18, v252, 24
	v_readlane_b32 s19, v252, 25
	v_readlane_b32 s20, v252, 26
	v_readlane_b32 s21, v252, 27
	v_readlane_b32 s24, v252, 30
	v_readlane_b32 s25, v252, 31
	v_readlane_b32 s26, v252, 32
	v_readlane_b32 s27, v252, 33
	s_waitcnt vmcnt(0) lgkmcnt(3)
	v_add_f32_e32 v2, v7, v2
	v_add_f32_e32 v2, v2, v3
	s_waitcnt lgkmcnt(2)
	v_add_f32_e32 v2, v2, v4
	v_add_f32_e32 v2, v2, v5
	s_waitcnt lgkmcnt(1)
	v_add_f32_e32 v2, v2, v8
	v_add_f32_e32 v2, v2, v9
	s_waitcnt lgkmcnt(0)
	v_add_f32_e32 v2, v2, v10
	v_add_f32_e32 v4, v2, v11
	v_lshl_add_u64 v[2:3], v[12:13], 2, s[86:87]
	global_store_dword v[2:3], v4, off
	s_branch .LBB0_532
